# E38: G1-odd rope epilogue cos/sin loads hoisted (7 of 8 rows) with counted waits, on top of E37
# speedup vs baseline: 1.0051x; 1.0015x over previous
;   __device__ __forceinline__ void operator()(const f32x4 (&acc)[2][2][4][2], const pg8::Unit& u, int wr, int wc, int fr, int fq) const {
;     ...
;     if (pn == 6 || pn == 7) {
;       float* dst = pn == 6 ? RQ : RK; const float sc = pn == 6 ? 1.f : 0.125f; const int ax = wc & 1;
;       const int row0 = u.pm * 256 + wr * 64 + fr, colt = wc * 32 + 4 * fq;
; #pragma unroll
;       for (int ai = 0; ai < 2; ++ai)
; #pragma unroll
;         for (int m = 0; m < 4; ++m) { const int row = row0 + ai * 128 + m * 16;
;           f32x4 cs = {1.f, 1.f, 1.f, 1.f}, sn = {0.f, 0.f, 0.f, 0.f};
;           if (row >= NCTX) { const int t = row - NCTX; const int pos = ax ? (t & 63) : (t >> 6); const float* rp = ROPE + pos * 32 + (4 * fq) * 2;
;             const f32x4 a = *(const f32x4*)rp, b = *(const f32x4*)(rp + 4); cs = (f32x4){a[0], a[2], b[0], b[2]}; sn = (f32x4){a[1], a[3], b[1], b[3]}; }
; #pragma unroll
;           for (int bj = 0; bj < 2; ++bj) { const f32x4 x0 = acc[ai][bj][m][0] * sc, x1 = acc[ai][bj][m][1] * sc;
;             const f32x4 o0 = x0 * cs - x1 * sn, o1 = x1 * cs + x0 * sn; const int col = colt + bj * 128;
;             *(f32x4*)(dst + (size_t)row * 256 + col) = o0; *(f32x4*)(dst + (size_t)row * 256 + col + 16) = o1; } }
.LBB0_1008:
	s_and_b64 vcc, exec, s[10:11]
	s_movk_i32 s79, 0x40ff
	s_movk_i32 s78, 0x2000
	s_cbranch_vccz .LBB0_613
	s_lshl_b32 s17, s66, 8
	s_add_i32 s17, s17, s69
	v_or_b32_e32 v152, s17, v143
	s_add_i32 s4, s17, 0xffffff00
	s_lshr_b32 s18, s4, 6
	s_add_i32 s100, s18, 2
	s_cmp_gt_u32 s17, 0xff
	s_cbranch_scc0 .Lrope_nohoist
	v_mov_b32_e32 v252, s18
	v_cndmask_b32_e64 v252, v143, v252, s[6:7]
	s_nop 0
	v_lshlrev_b32_e32 v250, 5, v252
	v_mov_b32_e32 v251, v144
	v_lshl_add_u64 v[250:251], v[250:251], 2, v[146:147]
	global_load_dwordx4 v[170:173], v[250:251], off
	global_load_dwordx4 v[174:177], v[250:251], off offset:16
	v_mov_b32_e32 v252, s18
	v_cndmask_b32_e64 v252, v161, v252, s[6:7]
	s_nop 0
	v_lshlrev_b32_e32 v250, 5, v252
	v_mov_b32_e32 v251, v144
	v_lshl_add_u64 v[250:251], v[250:251], 2, v[146:147]
	global_load_dwordx4 v[178:181], v[250:251], off
	global_load_dwordx4 v[182:185], v[250:251], off offset:16
	v_mov_b32_e32 v252, s18
	v_cndmask_b32_e64 v252, v162, v252, s[6:7]
	s_nop 0
	v_lshlrev_b32_e32 v250, 5, v252
	v_mov_b32_e32 v251, v144
	v_lshl_add_u64 v[250:251], v[250:251], 2, v[146:147]
	global_load_dwordx4 v[198:201], v[250:251], off
	global_load_dwordx4 v[214:217], v[250:251], off offset:16
	v_mov_b32_e32 v252, s18
	v_cndmask_b32_e64 v252, v163, v252, s[6:7]
	s_nop 0
	v_lshlrev_b32_e32 v250, 5, v252
	v_mov_b32_e32 v251, v144
	v_lshl_add_u64 v[250:251], v[250:251], 2, v[146:147]
	global_load_dwordx4 v[218:221], v[250:251], off
	global_load_dwordx4 v[222:225], v[250:251], off offset:16
	v_mov_b32_e32 v252, s100
	v_cndmask_b32_e64 v252, v143, v252, s[6:7]
	s_nop 0
	v_lshlrev_b32_e32 v250, 5, v252
	v_mov_b32_e32 v251, v144
	v_lshl_add_u64 v[250:251], v[250:251], 2, v[146:147]
	global_load_dwordx4 v[226:229], v[250:251], off
	global_load_dwordx4 v[230:233], v[250:251], off offset:16
	v_mov_b32_e32 v252, s100
	v_cndmask_b32_e64 v252, v161, v252, s[6:7]
	s_nop 0
	v_lshlrev_b32_e32 v250, 5, v252
	v_mov_b32_e32 v251, v144
	v_lshl_add_u64 v[250:251], v[250:251], 2, v[146:147]
	global_load_dwordx4 v[234:237], v[250:251], off
	global_load_dwordx4 v[238:241], v[250:251], off offset:16
	v_mov_b32_e32 v252, s100
	v_cndmask_b32_e64 v252, v162, v252, s[6:7]
	s_nop 0
	v_lshlrev_b32_e32 v250, 5, v252
	v_mov_b32_e32 v251, v144
	v_lshl_add_u64 v[250:251], v[250:251], 2, v[146:147]
	global_load_dwordx4 v[242:245], v[250:251], off
	global_load_dwordx4 v[246:249], v[250:251], off offset:16
.Lrope_nohoist:
	v_cmp_lt_i32_e32 vcc, s81, v152
	v_mov_b32_e32 v128, 1.0
	v_mov_b32_e32 v154, 0
	v_mov_b32_e32 v156, 0
	v_mov_b32_e32 v157, 0
	v_mov_b32_e32 v158, 0
	v_mov_b32_e32 v159, 0
	v_mov_b32_e32 v130, 1.0
	v_mov_b32_e32 v131, 1.0
	v_mov_b32_e32 v134, 1.0
	v_mov_b32_e32 v135, 1.0
	s_and_saveexec_b64 s[10:11], vcc
	s_cbranch_execz .LBB0_1011
	s_waitcnt vmcnt(12)
	v_mov_b32_e32 v156, v171
	v_mov_b32_e32 v157, v173
	v_mov_b32_e32 v158, v175
	v_mov_b32_e32 v159, v177
	v_mov_b32_e32 v131, v172
	v_mov_b32_e32 v135, v176
	v_mov_b32_e32 v130, v170
	v_mov_b32_e32 v134, v174
.LBB0_1011:
	s_or_b64 exec, exec, s[10:11]
	s_cmp_eq_u32 s38, 6
	s_cselect_b64 s[4:5], -1, 0
	v_mov_b32_e32 v129, 0x3e000000
	v_cndmask_b32_e64 v132, v129, 1.0, s[4:5]
	s_and_b64 s[4:5], s[4:5], exec
	v_ashrrev_i32_e32 v153, 31, v152
	v_pk_mul_f32 v[120:121], v[132:133], v[120:121] op_sel_hi:[0,1]
	s_cselect_b32 s11, s27, s83
	s_cselect_b32 s10, s26, s82
	v_lshlrev_b64 v[136:137], 10, v[152:153]
	v_pk_mul_f32 v[166:167], v[132:133], v[124:125] op_sel_hi:[0,1]
	v_pk_mul_f32 v[168:169], v[132:133], v[122:123] op_sel_hi:[0,1]
	v_pk_mul_f32 v[122:123], v[120:121], v[156:157]
	v_pk_mul_f32 v[120:121], v[120:121], v[130:131]
	v_lshl_add_u64 v[136:137], s[10:11], 0, v[136:137]
	v_pk_mul_f32 v[126:127], v[132:133], v[126:127] op_sel_hi:[0,1]
	v_pk_mul_f32 v[124:125], v[168:169], v[158:159]
	v_pk_fma_f32 v[122:123], v[166:167], v[130:131], v[122:123] neg_lo:[0,0,1] neg_hi:[0,0,1]
	v_pk_mul_f32 v[168:169], v[168:169], v[134:135]
	v_pk_fma_f32 v[166:167], v[166:167], v[156:157], v[120:121]
	v_lshlrev_b32_e32 v120, 2, v142
	v_mov_b32_e32 v121, v144
	v_pk_fma_f32 v[124:125], v[126:127], v[134:135], v[124:125] neg_lo:[0,0,1] neg_hi:[0,0,1]
	v_pk_fma_f32 v[168:169], v[126:127], v[158:159], v[168:169]
	v_lshl_add_u64 v[126:127], v[136:137], 0, v[120:121]
	global_store_dwordx4 v[126:127], v[122:125], off
	global_store_dwordx4 v[126:127], v[166:169], off offset:64
	v_pk_mul_f32 v[118:119], v[132:133], v[118:119] op_sel_hi:[0,1]
	v_pk_mul_f32 v[122:123], v[132:133], v[114:115] op_sel_hi:[0,1]
	v_pk_mul_f32 v[124:125], v[132:133], v[112:113] op_sel_hi:[0,1]
	v_pk_mul_f32 v[116:117], v[132:133], v[116:117] op_sel_hi:[0,1]
	v_pk_mul_f32 v[112:113], v[124:125], v[156:157]
	v_pk_mul_f32 v[114:115], v[122:123], v[158:159]
	v_pk_mul_f32 v[122:123], v[122:123], v[134:135]
	v_pk_fma_f32 v[114:115], v[118:119], v[134:135], v[114:115] neg_lo:[0,0,1] neg_hi:[0,0,1]
	v_pk_fma_f32 v[112:113], v[116:117], v[130:131], v[112:113] neg_lo:[0,0,1] neg_hi:[0,0,1]
	v_pk_mul_f32 v[124:125], v[124:125], v[130:131]
	v_pk_fma_f32 v[118:119], v[118:119], v[158:159], v[122:123]
	v_pk_fma_f32 v[116:117], v[116:117], v[156:157], v[124:125]
	global_store_dwordx4 v[126:127], v[112:115], off offset:512
	global_store_dwordx4 v[126:127], v[116:119], off offset:576
	v_mov_b32_e32 v155, 0
	v_mov_b32_e32 v129, 1.0
	v_or_b32_e32 v118, 16, v152
	v_cmp_lt_i32_e32 vcc, s81, v118
	v_mov_b32_e32 v116, 0
	v_mov_b32_e32 v117, 0
	v_mov_b32_e32 v112, 1.0
	v_mov_b32_e32 v113, 1.0
	s_and_saveexec_b64 s[12:13], vcc
	s_cbranch_execz .LBB0_1013
	s_waitcnt vmcnt(14)
	v_mov_b32_e32 v154, v179
	v_mov_b32_e32 v155, v181
	v_mov_b32_e32 v116, v183
	v_mov_b32_e32 v117, v185
	v_mov_b32_e32 v129, v180
	v_mov_b32_e32 v113, v184
	v_mov_b32_e32 v128, v178
	v_mov_b32_e32 v112, v182
;   __device__ __forceinline__ void operator()(const f32x4 (&acc)[2][2][4][2], const pg8::Unit& u, int wr, int wc, int fr, int fq) const {
;     ...
;         for (int m = 0; m < 4; ++m) { const int row = row0 + ai * 128 + m * 16;
;           f32x4 cs = {1.f, 1.f, 1.f, 1.f}, sn = {0.f, 0.f, 0.f, 0.f};
;           if (row >= NCTX) { const int t = row - NCTX; const int pos = ax ? (t & 63) : (t >> 6); const float* rp = ROPE + pos * 32 + (4 * fq) * 2;
;             const f32x4 a = *(const f32x4*)rp, b = *(const f32x4*)(rp + 4); cs = (f32x4){a[0], a[2], b[0], b[2]}; sn = (f32x4){a[1], a[3], b[1], b[3]}; }
; #pragma unroll
;           for (int bj = 0; bj < 2; ++bj) { const f32x4 x0 = acc[ai][bj][m][0] * sc, x1 = acc[ai][bj][m][1] * sc;
;             const f32x4 o0 = x0 * cs - x1 * sn, o1 = x1 * cs + x0 * sn; const int col = colt + bj * 128;
;             *(f32x4*)(dst + (size_t)row * 256 + col) = o0; *(f32x4*)(dst + (size_t)row * 256 + col + 16) = o1; } }
.LBB0_1013:
	s_or_b64 exec, exec, s[12:13]
	v_ashrrev_i32_e32 v119, 31, v118
	v_lshlrev_b64 v[114:115], 10, v[118:119]
	v_mov_b32_e32 v133, v132
	v_lshl_add_u64 v[118:119], s[10:11], 0, v[114:115]
	v_mov_b32_e32 v114, v132
	v_mov_b32_e32 v115, v132
	v_pk_mul_f32 v[122:123], v[114:115], v[106:107]
	v_pk_mul_f32 v[124:125], v[132:133], v[104:105]
	v_pk_mul_f32 v[110:111], v[114:115], v[110:111]
	v_pk_mul_f32 v[108:109], v[132:133], v[108:109]
	v_pk_mul_f32 v[104:105], v[124:125], v[154:155]
	v_pk_mul_f32 v[106:107], v[122:123], v[116:117]
	v_pk_fma_f32 v[104:105], v[108:109], v[128:129], v[104:105] neg_lo:[0,0,1] neg_hi:[0,0,1]
	v_pk_fma_f32 v[106:107], v[110:111], v[112:113], v[106:107] neg_lo:[0,0,1] neg_hi:[0,0,1]
	v_pk_mul_f32 v[124:125], v[124:125], v[128:129]
	v_pk_mul_f32 v[122:123], v[122:123], v[112:113]
	v_lshl_add_u64 v[118:119], v[118:119], 0, v[120:121]
	v_pk_fma_f32 v[110:111], v[110:111], v[116:117], v[122:123]
	v_pk_fma_f32 v[108:109], v[108:109], v[154:155], v[124:125]
	global_store_dwordx4 v[118:119], v[104:107], off
	global_store_dwordx4 v[118:119], v[108:111], off offset:64
	v_pk_mul_f32 v[102:103], v[114:115], v[102:103]
	v_pk_mul_f32 v[104:105], v[114:115], v[98:99]
	v_pk_mul_f32 v[106:107], v[132:133], v[96:97]
	v_pk_mul_f32 v[100:101], v[132:133], v[100:101]
	v_pk_mul_f32 v[96:97], v[106:107], v[154:155]
	v_pk_mul_f32 v[98:99], v[104:105], v[116:117]
	v_pk_mul_f32 v[104:105], v[104:105], v[112:113]
	v_pk_fma_f32 v[98:99], v[102:103], v[112:113], v[98:99] neg_lo:[0,0,1] neg_hi:[0,0,1]
	v_pk_fma_f32 v[96:97], v[100:101], v[128:129], v[96:97] neg_lo:[0,0,1] neg_hi:[0,0,1]
	v_pk_mul_f32 v[106:107], v[106:107], v[128:129]
	v_pk_fma_f32 v[102:103], v[102:103], v[116:117], v[104:105]
	v_or_b32_e32 v112, 32, v152
	v_pk_fma_f32 v[100:101], v[100:101], v[154:155], v[106:107]
	global_store_dwordx4 v[118:119], v[96:99], off offset:512
	global_store_dwordx4 v[118:119], v[100:103], off offset:576
	v_cmp_lt_i32_e32 vcc, s81, v112
	v_mov_b32_e32 v96, 1.0
	v_mov_b32_e32 v106, 0
	v_mov_b32_e32 v108, 0
	v_mov_b32_e32 v109, 0
	v_mov_b32_e32 v110, 0
	v_mov_b32_e32 v111, 0
	v_mov_b32_e32 v98, 1.0
	v_mov_b32_e32 v99, 1.0
	v_mov_b32_e32 v102, 1.0
	v_mov_b32_e32 v103, 1.0
	s_and_saveexec_b64 s[12:13], vcc
	s_cbranch_execz .LBB0_1015
	s_waitcnt vmcnt(16)
	v_mov_b32_e32 v108, v199
	v_mov_b32_e32 v109, v201
	v_mov_b32_e32 v110, v215
	v_mov_b32_e32 v111, v217
	v_mov_b32_e32 v99, v200
	v_mov_b32_e32 v103, v216
	v_mov_b32_e32 v98, v198
	v_mov_b32_e32 v102, v214
.LBB0_1015:
	s_or_b64 exec, exec, s[12:13]
	v_ashrrev_i32_e32 v113, 31, v112
	v_lshlrev_b64 v[100:101], 10, v[112:113]
	v_pk_mul_f32 v[104:105], v[114:115], v[90:91]
	v_pk_mul_f32 v[112:113], v[132:133], v[88:89]
	v_lshl_add_u64 v[100:101], s[10:11], 0, v[100:101]
	v_pk_mul_f32 v[94:95], v[114:115], v[94:95]
	v_pk_mul_f32 v[92:93], v[132:133], v[92:93]
	v_pk_mul_f32 v[88:89], v[112:113], v[108:109]
	v_pk_mul_f32 v[90:91], v[104:105], v[110:111]
	v_mov_b32_e32 v121, v144
	v_pk_fma_f32 v[90:91], v[94:95], v[102:103], v[90:91] neg_lo:[0,0,1] neg_hi:[0,0,1]
	v_pk_fma_f32 v[88:89], v[92:93], v[98:99], v[88:89] neg_lo:[0,0,1] neg_hi:[0,0,1]
	v_pk_mul_f32 v[112:113], v[112:113], v[98:99]
	v_pk_mul_f32 v[104:105], v[104:105], v[102:103]
	v_lshl_add_u64 v[100:101], v[100:101], 0, v[120:121]
	v_pk_fma_f32 v[94:95], v[94:95], v[110:111], v[104:105]
	v_pk_fma_f32 v[92:93], v[92:93], v[108:109], v[112:113]
	global_store_dwordx4 v[100:101], v[88:91], off
	global_store_dwordx4 v[100:101], v[92:95], off offset:64
	v_pk_mul_f32 v[86:87], v[114:115], v[86:87]
	v_pk_mul_f32 v[88:89], v[114:115], v[82:83]
	v_pk_mul_f32 v[90:91], v[132:133], v[80:81]
	v_pk_mul_f32 v[84:85], v[132:133], v[84:85]
	v_pk_mul_f32 v[80:81], v[90:91], v[108:109]
	v_pk_mul_f32 v[82:83], v[88:89], v[110:111]
	v_pk_mul_f32 v[88:89], v[88:89], v[102:103]
	v_pk_fma_f32 v[82:83], v[86:87], v[102:103], v[82:83] neg_lo:[0,0,1] neg_hi:[0,0,1]
	v_pk_fma_f32 v[80:81], v[84:85], v[98:99], v[80:81] neg_lo:[0,0,1] neg_hi:[0,0,1]
	v_pk_mul_f32 v[90:91], v[90:91], v[98:99]
	v_pk_fma_f32 v[86:87], v[86:87], v[110:111], v[88:89]
	v_pk_fma_f32 v[84:85], v[84:85], v[108:109], v[90:91]
	global_store_dwordx4 v[100:101], v[80:83], off offset:512
	global_store_dwordx4 v[100:101], v[84:87], off offset:576
	v_mov_b32_e32 v107, 0
	v_mov_b32_e32 v97, 1.0
	v_or_b32_e32 v86, 48, v152
	v_cmp_lt_i32_e32 vcc, s81, v86
	v_mov_b32_e32 v84, 0
	v_mov_b32_e32 v85, 0
	v_mov_b32_e32 v80, 1.0
	v_mov_b32_e32 v81, 1.0
	s_and_saveexec_b64 s[12:13], vcc
	s_cbranch_execz .LBB0_1017
	s_waitcnt vmcnt(18)
	v_mov_b32_e32 v106, v219
	v_mov_b32_e32 v107, v221
	v_mov_b32_e32 v84, v223
	v_mov_b32_e32 v85, v225
	v_mov_b32_e32 v97, v220
	v_mov_b32_e32 v81, v224
	v_mov_b32_e32 v96, v218
	v_mov_b32_e32 v80, v222
;   __device__ __forceinline__ void operator()(const f32x4 (&acc)[2][2][4][2], const pg8::Unit& u, int wr, int wc, int fr, int fq) const {
;     ...
;         for (int m = 0; m < 4; ++m) { const int row = row0 + ai * 128 + m * 16;
;           f32x4 cs = {1.f, 1.f, 1.f, 1.f}, sn = {0.f, 0.f, 0.f, 0.f};
;           if (row >= NCTX) { const int t = row - NCTX; const int pos = ax ? (t & 63) : (t >> 6); const float* rp = ROPE + pos * 32 + (4 * fq) * 2;
;             const f32x4 a = *(const f32x4*)rp, b = *(const f32x4*)(rp + 4); cs = (f32x4){a[0], a[2], b[0], b[2]}; sn = (f32x4){a[1], a[3], b[1], b[3]}; }
; #pragma unroll
;           for (int bj = 0; bj < 2; ++bj) { const f32x4 x0 = acc[ai][bj][m][0] * sc, x1 = acc[ai][bj][m][1] * sc;
;             const f32x4 o0 = x0 * cs - x1 * sn, o1 = x1 * cs + x0 * sn; const int col = colt + bj * 128;
;             *(f32x4*)(dst + (size_t)row * 256 + col) = o0; *(f32x4*)(dst + (size_t)row * 256 + col + 16) = o1; } }
.LBB0_1017:
	s_or_b64 exec, exec, s[12:13]
	v_ashrrev_i32_e32 v87, 31, v86
	v_lshlrev_b64 v[82:83], 10, v[86:87]
	v_lshl_add_u64 v[86:87], s[10:11], 0, v[82:83]
	v_mov_b32_e32 v82, v132
	v_mov_b32_e32 v83, v132
	v_pk_mul_f32 v[88:89], v[82:83], v[74:75]
	v_pk_mul_f32 v[90:91], v[132:133], v[72:73]
	v_pk_mul_f32 v[78:79], v[82:83], v[78:79]
	v_pk_mul_f32 v[76:77], v[132:133], v[76:77]
	v_pk_mul_f32 v[72:73], v[90:91], v[106:107]
	v_pk_mul_f32 v[74:75], v[88:89], v[84:85]
	v_pk_fma_f32 v[72:73], v[76:77], v[96:97], v[72:73] neg_lo:[0,0,1] neg_hi:[0,0,1]
	v_pk_fma_f32 v[74:75], v[78:79], v[80:81], v[74:75] neg_lo:[0,0,1] neg_hi:[0,0,1]
	v_pk_mul_f32 v[90:91], v[90:91], v[96:97]
	v_pk_mul_f32 v[88:89], v[88:89], v[80:81]
	v_lshl_add_u64 v[86:87], v[86:87], 0, v[120:121]
	v_pk_fma_f32 v[78:79], v[78:79], v[84:85], v[88:89]
	v_pk_fma_f32 v[76:77], v[76:77], v[106:107], v[90:91]
	global_store_dwordx4 v[86:87], v[72:75], off
	global_store_dwordx4 v[86:87], v[76:79], off offset:64
	v_pk_mul_f32 v[70:71], v[82:83], v[70:71]
	v_pk_mul_f32 v[72:73], v[82:83], v[66:67]
	v_pk_mul_f32 v[74:75], v[132:133], v[64:65]
	v_pk_mul_f32 v[68:69], v[132:133], v[68:69]
	v_pk_mul_f32 v[64:65], v[74:75], v[106:107]
	v_pk_mul_f32 v[66:67], v[72:73], v[84:85]
	v_pk_mul_f32 v[72:73], v[72:73], v[80:81]
	v_pk_fma_f32 v[66:67], v[70:71], v[80:81], v[66:67] neg_lo:[0,0,1] neg_hi:[0,0,1]
	v_pk_fma_f32 v[64:65], v[68:69], v[96:97], v[64:65] neg_lo:[0,0,1] neg_hi:[0,0,1]
	v_pk_mul_f32 v[74:75], v[74:75], v[96:97]
	v_pk_fma_f32 v[70:71], v[70:71], v[84:85], v[72:73]
	s_addk_i32 s17, 0xff80
	s_movk_i32 s4, 0x7f
	v_pk_fma_f32 v[68:69], v[68:69], v[106:107], v[74:75]
	global_store_dwordx4 v[86:87], v[64:67], off offset:512
	global_store_dwordx4 v[86:87], v[68:71], off offset:576
	s_lshr_b32 s17, s17, 6
	v_cmp_lt_i32_e32 vcc, s4, v152
	v_mov_b32_e32 v64, 1.0
	v_mov_b32_e32 v74, 0
	v_mov_b32_e32 v76, 0
	v_mov_b32_e32 v77, 0
	v_mov_b32_e32 v78, 0
	v_mov_b32_e32 v79, 0
	v_mov_b32_e32 v66, 1.0
	v_mov_b32_e32 v67, 1.0
	v_mov_b32_e32 v70, 1.0
	v_mov_b32_e32 v71, 1.0
	s_and_saveexec_b64 s[12:13], vcc
	s_cbranch_execz .LBB0_1019
	s_waitcnt vmcnt(20)
	v_mov_b32_e32 v76, v227
	v_mov_b32_e32 v77, v229
	v_mov_b32_e32 v78, v231
	v_mov_b32_e32 v79, v233
	v_mov_b32_e32 v67, v228
	v_mov_b32_e32 v71, v232
	v_mov_b32_e32 v66, v226
	v_mov_b32_e32 v70, v230
.LBB0_1019:
	s_or_b64 exec, exec, s[12:13]
	v_lshlrev_b64 v[68:69], 10, v[152:153]
	v_pk_mul_f32 v[56:57], v[132:133], v[56:57]
	v_lshl_add_u64 v[68:69], s[10:11], 0, v[68:69]
	v_pk_mul_f32 v[72:73], v[132:133], v[60:61]
	v_pk_mul_f32 v[80:81], v[82:83], v[58:59]
	v_pk_mul_f32 v[58:59], v[56:57], v[76:77]
	v_pk_mul_f32 v[56:57], v[56:57], v[66:67]
	v_mov_b32_e32 v121, v144
	v_pk_fma_f32 v[84:85], v[72:73], v[76:77], v[56:57]
	v_lshl_add_u64 v[56:57], v[68:69], 0, v[120:121]
	v_pk_mul_f32 v[62:63], v[82:83], v[62:63]
	v_pk_mul_f32 v[60:61], v[80:81], v[78:79]
	v_add_co_u32_e32 v68, vcc, s31, v56
	v_pk_fma_f32 v[60:61], v[62:63], v[70:71], v[60:61] neg_lo:[0,0,1] neg_hi:[0,0,1]
	v_pk_fma_f32 v[58:59], v[72:73], v[66:67], v[58:59] neg_lo:[0,0,1] neg_hi:[0,0,1]
	v_pk_mul_f32 v[80:81], v[80:81], v[70:71]
	s_mov_b64 s[4:5], 0x20000
	v_addc_co_u32_e32 v69, vcc, 0, v57, vcc
	v_pk_fma_f32 v[86:87], v[62:63], v[78:79], v[80:81]
	v_lshl_add_u64 v[62:63], v[56:57], 0, s[4:5]
	global_store_dwordx4 v[68:69], v[58:61], off
	global_store_dwordx4 v[62:63], v[84:87], off offset:64
	v_pk_mul_f32 v[54:55], v[82:83], v[54:55]
	v_pk_mul_f32 v[58:59], v[82:83], v[50:51]
	v_pk_mul_f32 v[60:61], v[132:133], v[48:49]
	v_pk_mul_f32 v[52:53], v[132:133], v[52:53]
	v_pk_mul_f32 v[48:49], v[60:61], v[76:77]
	v_pk_mul_f32 v[50:51], v[58:59], v[78:79]
	v_pk_mul_f32 v[60:61], v[60:61], v[66:67]
	v_pk_fma_f32 v[50:51], v[54:55], v[70:71], v[50:51] neg_lo:[0,0,1] neg_hi:[0,0,1]
	v_pk_fma_f32 v[48:49], v[52:53], v[66:67], v[48:49] neg_lo:[0,0,1] neg_hi:[0,0,1]
	v_pk_mul_f32 v[58:59], v[58:59], v[70:71]
	v_pk_fma_f32 v[52:53], v[52:53], v[76:77], v[60:61]
	s_movk_i32 s4, 0x6f
	v_pk_fma_f32 v[54:55], v[54:55], v[78:79], v[58:59]
	global_store_dwordx4 v[62:63], v[48:51], off offset:512
	global_store_dwordx4 v[62:63], v[52:55], off offset:576
	v_cmp_lt_i32_e32 vcc, s4, v152
	v_mov_b32_e32 v75, 0
	v_mov_b32_e32 v52, 0
	v_mov_b32_e32 v53, 0
	v_mov_b32_e32 v65, 1.0
	v_mov_b32_e32 v48, 1.0
	v_mov_b32_e32 v49, 1.0
	s_and_saveexec_b64 s[12:13], vcc
	s_cbranch_execz .LBB0_1021
	s_waitcnt vmcnt(22)
	v_mov_b32_e32 v74, v235
	v_mov_b32_e32 v75, v237
	v_mov_b32_e32 v52, v239
	v_mov_b32_e32 v53, v241
	v_mov_b32_e32 v65, v236
	v_mov_b32_e32 v49, v240
	v_mov_b32_e32 v64, v234
	v_mov_b32_e32 v48, v238
.LBB0_1021:
	s_or_b64 exec, exec, s[12:13]
	v_mov_b32_e32 v50, v132
	v_mov_b32_e32 v51, v132
	v_pk_mul_f32 v[54:55], v[50:51], v[42:43]
	v_pk_mul_f32 v[46:47], v[50:51], v[46:47]
	v_pk_mul_f32 v[42:43], v[54:55], v[52:53]
	v_pk_mul_f32 v[54:55], v[54:55], v[48:49]
	s_mov_b64 s[4:5], 0x24000
	v_pk_mul_f32 v[58:59], v[132:133], v[40:41]
	v_pk_fma_f32 v[42:43], v[46:47], v[48:49], v[42:43] neg_lo:[0,0,1] neg_hi:[0,0,1]
	v_pk_fma_f32 v[46:47], v[46:47], v[52:53], v[54:55]
	v_lshl_add_u64 v[54:55], v[56:57], 0, s[4:5]
	s_mov_b32 s4, 0x24000
	v_pk_mul_f32 v[44:45], v[132:133], v[44:45]
	v_pk_mul_f32 v[40:41], v[58:59], v[74:75]
	v_add_co_u32_e32 v56, vcc, s4, v56
	v_pk_fma_f32 v[40:41], v[44:45], v[64:65], v[40:41] neg_lo:[0,0,1] neg_hi:[0,0,1]
	v_pk_mul_f32 v[58:59], v[58:59], v[64:65]
	v_addc_co_u32_e32 v57, vcc, 0, v57, vcc
	v_pk_fma_f32 v[44:45], v[44:45], v[74:75], v[58:59]
	global_store_dwordx4 v[56:57], v[40:43], off
	global_store_dwordx4 v[54:55], v[44:47], off offset:64
	v_pk_mul_f32 v[38:39], v[50:51], v[38:39]
	v_pk_mul_f32 v[40:41], v[50:51], v[34:35]
	v_pk_mul_f32 v[42:43], v[132:133], v[32:33]
	v_pk_mul_f32 v[36:37], v[132:133], v[36:37]
	v_pk_mul_f32 v[32:33], v[42:43], v[74:75]
	v_pk_mul_f32 v[34:35], v[40:41], v[52:53]
	v_pk_mul_f32 v[40:41], v[40:41], v[48:49]
	v_pk_fma_f32 v[34:35], v[38:39], v[48:49], v[34:35] neg_lo:[0,0,1] neg_hi:[0,0,1]
	v_pk_fma_f32 v[32:33], v[36:37], v[64:65], v[32:33] neg_lo:[0,0,1] neg_hi:[0,0,1]
	v_pk_mul_f32 v[42:43], v[42:43], v[64:65]
	v_pk_fma_f32 v[38:39], v[38:39], v[52:53], v[40:41]
	s_movk_i32 s4, 0x5f
	v_pk_fma_f32 v[36:37], v[36:37], v[74:75], v[42:43]
	global_store_dwordx4 v[54:55], v[32:35], off offset:512
	global_store_dwordx4 v[54:55], v[36:39], off offset:576
	v_cmp_lt_i32_e32 vcc, s4, v152
	v_mov_b32_e32 v32, 1.0
	v_mov_b32_e32 v42, 0
	v_mov_b32_e32 v44, 0
	v_mov_b32_e32 v45, 0
	v_mov_b32_e32 v46, 0
	v_mov_b32_e32 v47, 0
	v_mov_b32_e32 v34, 1.0
	v_mov_b32_e32 v35, 1.0
	v_mov_b32_e32 v38, 1.0
	v_mov_b32_e32 v39, 1.0
	s_and_saveexec_b64 s[12:13], vcc
	s_cbranch_execz .LBB0_1023
	s_waitcnt vmcnt(24)
	v_mov_b32_e32 v44, v243
	v_mov_b32_e32 v45, v245
	v_mov_b32_e32 v46, v247
	v_mov_b32_e32 v47, v249
	v_mov_b32_e32 v35, v244
	v_mov_b32_e32 v39, v248
	v_mov_b32_e32 v34, v242
	v_mov_b32_e32 v38, v246
